# prio raise window variant g (waves 4-7) + S2 hand schedule + ccdma + P0 transposes MLP
# speedup vs baseline: 1.0287x; 1.0062x over previous
; #define LOADV(dst, ks_) do { _Pragma("unroll") for (int dvb = 0; dvb < 4; ++dvb) { dst[2 * dvb] = vtr(vp + dvb * 4096 + (ks_) * 1024); dst[2 * dvb + 1] = vtr(vp + dvb * 4096 + (ks_) * 1024 + 512); } } while (0)
; #define MF4(src, pfrag) do { _Pragma("unroll") for (int dvb = 0; dvb < 4; ++dvb) { \
;         const bf16x8 vf_ = __builtin_shufflevector(src[2 * dvb], src[2 * dvb + 1], 0, 1, 2, 3, 4, 5, 6, 7); o[dvb] = MFMA32(vf_, pfrag, o[dvb]); } } while (0)
; #define EXPQ(S, lo_, RS, PF) do { _Pragma("unroll") for (int i = lo_; i < lo_ + 8; ++i) { S[i] = ex2(S[i]); RS += S[i]; } \
;               u32x4 w_; w_.x = pk2(S[lo_], S[lo_ + 1]); w_.y = pk2(S[lo_ + 2], S[lo_ + 3]); w_.z = pk2(S[lo_ + 4], S[lo_ + 5]); w_.w = pk2(S[lo_ + 6], S[lo_ + 7]); PF = __builtin_bit_cast(bf16x8, w_); } while (0)
; DI void attn_unit(const Params& p, int bh, int qb, char* lds, float lam, int tid, int lane, int wid, const bool build_tab) {
;     ...
;             float rs0 = 0.f, rs1 = 0.f;
;     ...
;             EXPQ(s0, 0, rs0, pf[0]);
;             LOADV(vb, 1);
;             MF4(va, pf[0]);
;             EXPQ(s0, 8, rs1, pf[1]);
;             LOADV(va, 2);
;             MF4(vb, pf[1]);
;             EXPQ(s1, 0, rs0, pf[2]);
;             LOADV(vb, 3);
;             MF4(va, pf[2]);
;             EXPQ(s1, 8, rs1, pf[3]);
;             MF4(vb, pf[3]);
;             l += rs0 + rs1;
.LBB0_359:
	s_setprio 0
	ds_read_b64_tr_b16 v[242:243], v220 offset:21504
	ds_read_b64_tr_b16 v[244:245], v220 offset:22016
	ds_read_b64_tr_b16 v[246:247], v220 offset:25600
	ds_read_b64_tr_b16 v[248:249], v220 offset:26112
	v_exp_f32_e32 v222, v96
	v_exp_f32_e32 v224, v97
	v_exp_f32_e32 v226, v98
	v_exp_f32_e32 v228, v99
	v_exp_f32_e32 v230, v100
	v_exp_f32_e32 v232, v101
	v_exp_f32_e32 v234, v102
	v_exp_f32_e32 v236, v103
	v_cvt_pk_bf16_f32 v96, v222, v224
	v_cvt_pk_bf16_f32 v97, v226, v228
	v_cvt_pk_bf16_f32 v98, v230, v232
	v_cvt_pk_bf16_f32 v99, v234, v236
	ds_read_b64_tr_b16 v[100:101], v220 offset:17408
	ds_read_b64_tr_b16 v[102:103], v220 offset:17920
	s_waitcnt lgkmcnt(12)
	v_mfma_f32_32x32x16_bf16 v[48:63], v[140:143], v[96:99], v[48:63]
	ds_read_b64_tr_b16 v[250:251], v220 offset:29696
	ds_read_b64_tr_b16 v[252:253], v220 offset:30208
	v_exp_f32_e32 v223, v104
	v_exp_f32_e32 v225, v105
	v_exp_f32_e32 v227, v106
	v_add_f32_e32 v221, v224, v222
	s_waitcnt lgkmcnt(12)
	v_mfma_f32_32x32x16_bf16 v[32:47], v[136:139], v[96:99], v[32:47]
	v_exp_f32_e32 v229, v107
	v_exp_f32_e32 v231, v108
	v_exp_f32_e32 v233, v109
	v_add_f32_e32 v221, v226, v221
	s_waitcnt lgkmcnt(10)
	v_mfma_f32_32x32x16_bf16 v[16:31], v[132:135], v[96:99], v[16:31]
	v_exp_f32_e32 v235, v110
	v_exp_f32_e32 v237, v111
	v_add_f32_e32 v221, v228, v221
	v_add_f32_e32 v221, v230, v221
	ds_read_b64_tr_b16 v[104:105], v220 offset:18432
	ds_read_b64_tr_b16 v[106:107], v220 offset:18944
	ds_read_b64_tr_b16 v[108:109], v220 offset:19456
	ds_read_b64_tr_b16 v[110:111], v220 offset:19968
	s_waitcnt lgkmcnt(12)
	v_mfma_f32_32x32x16_bf16 v[0:15], v[128:131], v[96:99], v[0:15]
	ds_read_b64_tr_b16 v[128:129], v220 offset:26624
	ds_read_b64_tr_b16 v[130:131], v220 offset:27136
	v_cvt_pk_bf16_f32 v96, v223, v225
	v_cvt_pk_bf16_f32 v97, v227, v229
	v_cvt_pk_bf16_f32 v98, v231, v233
	v_cvt_pk_bf16_f32 v99, v235, v237
	v_exp_f32_e32 v140, v84
	v_exp_f32_e32 v142, v85
	s_waitcnt lgkmcnt(8)
	v_mfma_f32_32x32x16_bf16 v[48:63], v[100:103], v[96:99], v[48:63]
	v_exp_f32_e32 v238, v86
	v_exp_f32_e32 v240, v87
	v_add_f32_e32 v221, v232, v221
	ds_read_b64_tr_b16 v[84:85], v220 offset:22528
	ds_read_b64_tr_b16 v[86:87], v220 offset:23040
	v_exp_f32_e32 v136, v82
	s_waitcnt lgkmcnt(14)
	v_mfma_f32_32x32x16_bf16 v[32:47], v[242:245], v[96:99], v[32:47]
	ds_read_b64_tr_b16 v[242:243], v220 offset:23552
	ds_read_b64_tr_b16 v[244:245], v220 offset:24064
	v_exp_f32_e32 v138, v83
	v_exp_f32_e32 v132, v80
	v_exp_f32_e32 v134, v81
	v_add_f32_e32 v221, v234, v221
	s_waitcnt lgkmcnt(14)
	v_mfma_f32_32x32x16_bf16 v[16:31], v[246:249], v[96:99], v[16:31]
	ds_read_b64_tr_b16 v[246:247], v220 offset:27648
	ds_read_b64_tr_b16 v[248:249], v220 offset:28160
	v_cvt_pk_bf16_f32 v80, v132, v134
	v_cvt_pk_bf16_f32 v81, v136, v138
	v_cvt_pk_bf16_f32 v82, v140, v142
	v_cvt_pk_bf16_f32 v83, v238, v240
	v_exp_f32_e32 v133, v88
	v_exp_f32_e32 v135, v89
	s_waitcnt lgkmcnt(12)
	v_mfma_f32_32x32x16_bf16 v[0:15], v[250:253], v[96:99], v[0:15]
	ds_read_b64_tr_b16 v[250:251], v220 offset:31744
	ds_read_b64_tr_b16 v[252:253], v220 offset:32256
	v_exp_f32_e32 v137, v90
	v_exp_f32_e32 v139, v91
	v_add_f32_e32 v221, v236, v221
	ds_read_b64_tr_b16 v[88:89], v220 offset:30720
	ds_read_b64_tr_b16 v[90:91], v220 offset:31232
	v_exp_f32_e32 v141, v92
	s_waitcnt lgkmcnt(14)
	v_mfma_f32_32x32x16_bf16 v[48:63], v[104:107], v[80:83], v[48:63]
	v_exp_f32_e32 v143, v93
	v_exp_f32_e32 v239, v94
	v_exp_f32_e32 v241, v95
	v_add_f32_e32 v221, v132, v221
	s_waitcnt lgkmcnt(8)
	v_mfma_f32_32x32x16_bf16 v[32:47], v[84:87], v[80:83], v[32:47]
	v_add_f32_e32 v93, v225, v223
	v_add_f32_e32 v221, v134, v221
	v_add_f32_e32 v93, v227, v93
	v_add_f32_e32 v221, v136, v221
	v_add_f32_e32 v93, v229, v93
	v_add_f32_e32 v221, v138, v221
	s_waitcnt lgkmcnt(10)
	v_mfma_f32_32x32x16_bf16 v[16:31], v[128:131], v[80:83], v[16:31]
	v_add_f32_e32 v93, v231, v93
	v_add_f32_e32 v221, v140, v221
	v_add_f32_e32 v93, v233, v93
	v_add_f32_e32 v221, v142, v221
	v_add_f32_e32 v93, v235, v93
	v_add_f32_e32 v221, v238, v221
	v_add_f32_e32 v93, v237, v93
	s_waitcnt lgkmcnt(0)
	v_mfma_f32_32x32x16_bf16 v[0:15], v[88:91], v[80:83], v[0:15]
	v_cvt_pk_bf16_f32 v80, v133, v135
	v_cvt_pk_bf16_f32 v81, v137, v139
	v_cvt_pk_bf16_f32 v82, v141, v143
	v_cvt_pk_bf16_f32 v83, v239, v241
	v_add_f32_e32 v221, v240, v221
	v_add_f32_e32 v93, v133, v93
	s_waitcnt lgkmcnt(12)
	v_mfma_f32_32x32x16_bf16 v[48:63], v[108:111], v[80:83], v[48:63]
	v_add_f32_e32 v93, v135, v93
	v_add_f32_e32 v93, v137, v93
	s_waitcnt lgkmcnt(6)
	v_mfma_f32_32x32x16_bf16 v[32:47], v[242:245], v[80:83], v[32:47]
	v_add_f32_e32 v93, v139, v93
	v_add_f32_e32 v93, v141, v93
	s_waitcnt lgkmcnt(4)
	v_mfma_f32_32x32x16_bf16 v[16:31], v[246:249], v[80:83], v[16:31]
	v_add_f32_e32 v93, v143, v93
	v_add_f32_e32 v93, v239, v93
	s_waitcnt lgkmcnt(2)
	v_mfma_f32_32x32x16_bf16 v[0:15], v[250:253], v[80:83], v[0:15]
	v_add_f32_e32 v93, v241, v93
	v_add_f32_e32 v221, v221, v93
	v_add_f32_e32 v146, v146, v221

; #define LOADV(dst, ks_) do { _Pragma("unroll") for (int dvb = 0; dvb < 4; ++dvb) { dst[2 * dvb] = vtr(vp + dvb * 4096 + (ks_) * 1024); dst[2 * dvb + 1] = vtr(vp + dvb * 4096 + (ks_) * 1024 + 512); } } while (0)
; #define MF4(src, pfrag) do { _Pragma("unroll") for (int dvb = 0; dvb < 4; ++dvb) { \
;         const bf16x8 vf_ = __builtin_shufflevector(src[2 * dvb], src[2 * dvb + 1], 0, 1, 2, 3, 4, 5, 6, 7); o[dvb] = MFMA32(vf_, pfrag, o[dvb]); } } while (0)
; #define EXPQ(S, lo_, RS, PF) do { _Pragma("unroll") for (int i = lo_; i < lo_ + 8; ++i) { S[i] = ex2(S[i]); RS += S[i]; } \
;               u32x4 w_; w_.x = pk2(S[lo_], S[lo_ + 1]); w_.y = pk2(S[lo_ + 2], S[lo_ + 3]); w_.z = pk2(S[lo_ + 4], S[lo_ + 5]); w_.w = pk2(S[lo_ + 6], S[lo_ + 7]); PF = __builtin_bit_cast(bf16x8, w_); } while (0)
; DI void attn_unit(const Params& p, int bh, int qb, char* lds, float lam, int tid, int lane, int wid, const bool build_tab) {
;     ...
;             float rs0 = 0.f, rs1 = 0.f;
;     ...
;             EXPQ(s0, 0, rs0, pf[0]);
;             LOADV(vb, 1);
;             MF4(va, pf[0]);
;             EXPQ(s0, 8, rs1, pf[1]);
;             LOADV(va, 2);
;             MF4(vb, pf[1]);
;             EXPQ(s1, 0, rs0, pf[2]);
;             LOADV(vb, 3);
;             MF4(va, pf[2]);
;             EXPQ(s1, 8, rs1, pf[3]);
;             MF4(vb, pf[3]);
;             l += rs0 + rs1;
.LBB0_379:
	s_setprio 0
	ds_read_b64_tr_b16 v[230:231], v177 offset:21504
	ds_read_b64_tr_b16 v[232:233], v177 offset:22016
	ds_read_b64_tr_b16 v[234:235], v177 offset:25600
	ds_read_b64_tr_b16 v[236:237], v177 offset:26112
	v_exp_f32_e32 v178, v96
	v_exp_f32_e32 v180, v97
	v_exp_f32_e32 v182, v98
	v_exp_f32_e32 v184, v99
	v_exp_f32_e32 v186, v100
	v_exp_f32_e32 v188, v101
	v_exp_f32_e32 v190, v102
	v_exp_f32_e32 v192, v103
	v_cvt_pk_bf16_f32 v96, v178, v180
	v_cvt_pk_bf16_f32 v97, v182, v184
	v_cvt_pk_bf16_f32 v98, v186, v188
	v_cvt_pk_bf16_f32 v99, v190, v192
	ds_read_b64_tr_b16 v[100:101], v177 offset:17408
	ds_read_b64_tr_b16 v[102:103], v177 offset:17920
	s_waitcnt lgkmcnt(12)
	v_mfma_f32_32x32x16_bf16 v[48:63], v[140:143], v[96:99], v[48:63]
	ds_read_b64_tr_b16 v[238:239], v177 offset:29696
	ds_read_b64_tr_b16 v[240:241], v177 offset:30208
	v_exp_f32_e32 v179, v104
	v_exp_f32_e32 v181, v105
	v_exp_f32_e32 v183, v106
	v_add_f32_e32 v242, v180, v178
	s_waitcnt lgkmcnt(12)
	v_mfma_f32_32x32x16_bf16 v[32:47], v[136:139], v[96:99], v[32:47]
	v_exp_f32_e32 v185, v107
	v_exp_f32_e32 v187, v108
	v_exp_f32_e32 v189, v109
	v_add_f32_e32 v242, v182, v242
	s_waitcnt lgkmcnt(10)
	v_mfma_f32_32x32x16_bf16 v[16:31], v[132:135], v[96:99], v[16:31]
	v_exp_f32_e32 v191, v110
	v_exp_f32_e32 v193, v111
	v_add_f32_e32 v242, v184, v242
	v_add_f32_e32 v242, v186, v242
	ds_read_b64_tr_b16 v[104:105], v177 offset:18432
	ds_read_b64_tr_b16 v[106:107], v177 offset:18944
	ds_read_b64_tr_b16 v[108:109], v177 offset:19456
	ds_read_b64_tr_b16 v[110:111], v177 offset:19968
	s_waitcnt lgkmcnt(12)
	v_mfma_f32_32x32x16_bf16 v[0:15], v[128:131], v[96:99], v[0:15]
	ds_read_b64_tr_b16 v[128:129], v177 offset:26624
	ds_read_b64_tr_b16 v[130:131], v177 offset:27136
	v_cvt_pk_bf16_f32 v96, v179, v181
	v_cvt_pk_bf16_f32 v97, v183, v185
	v_cvt_pk_bf16_f32 v98, v187, v189
	v_cvt_pk_bf16_f32 v99, v191, v193
	v_exp_f32_e32 v140, v84
	v_exp_f32_e32 v142, v85
	s_waitcnt lgkmcnt(8)
	v_mfma_f32_32x32x16_bf16 v[48:63], v[100:103], v[96:99], v[48:63]
	v_exp_f32_e32 v194, v86
	v_exp_f32_e32 v196, v87
	v_add_f32_e32 v242, v188, v242
	ds_read_b64_tr_b16 v[84:85], v177 offset:22528
	ds_read_b64_tr_b16 v[86:87], v177 offset:23040
	v_exp_f32_e32 v136, v82
	s_waitcnt lgkmcnt(14)
	v_mfma_f32_32x32x16_bf16 v[32:47], v[230:233], v[96:99], v[32:47]
	ds_read_b64_tr_b16 v[230:231], v177 offset:23552
	ds_read_b64_tr_b16 v[232:233], v177 offset:24064
	v_exp_f32_e32 v138, v83
	v_exp_f32_e32 v132, v80
	v_exp_f32_e32 v134, v81
	v_add_f32_e32 v242, v190, v242
	s_waitcnt lgkmcnt(14)
	v_mfma_f32_32x32x16_bf16 v[16:31], v[234:237], v[96:99], v[16:31]
	ds_read_b64_tr_b16 v[234:235], v177 offset:27648
	ds_read_b64_tr_b16 v[236:237], v177 offset:28160
	v_cvt_pk_bf16_f32 v80, v132, v134
	v_cvt_pk_bf16_f32 v81, v136, v138
	v_cvt_pk_bf16_f32 v82, v140, v142
	v_cvt_pk_bf16_f32 v83, v194, v196
	v_exp_f32_e32 v133, v88
	v_exp_f32_e32 v135, v89
	s_waitcnt lgkmcnt(12)
	v_mfma_f32_32x32x16_bf16 v[0:15], v[238:241], v[96:99], v[0:15]
	ds_read_b64_tr_b16 v[238:239], v177 offset:31744
	ds_read_b64_tr_b16 v[240:241], v177 offset:32256
	v_exp_f32_e32 v137, v90
	v_exp_f32_e32 v139, v91
	v_add_f32_e32 v242, v192, v242
	ds_read_b64_tr_b16 v[88:89], v177 offset:30720
	ds_read_b64_tr_b16 v[90:91], v177 offset:31232
	v_exp_f32_e32 v141, v92
	s_waitcnt lgkmcnt(14)
	v_mfma_f32_32x32x16_bf16 v[48:63], v[104:107], v[80:83], v[48:63]
	v_exp_f32_e32 v143, v93
	v_exp_f32_e32 v195, v94
	v_exp_f32_e32 v197, v95
	v_add_f32_e32 v242, v132, v242
	s_waitcnt lgkmcnt(8)
	v_mfma_f32_32x32x16_bf16 v[32:47], v[84:87], v[80:83], v[32:47]
	v_add_f32_e32 v243, v181, v179
	v_add_f32_e32 v242, v134, v242
	v_add_f32_e32 v243, v183, v243
	v_add_f32_e32 v242, v136, v242
	v_add_f32_e32 v243, v185, v243
	v_add_f32_e32 v242, v138, v242
	s_waitcnt lgkmcnt(10)
	v_mfma_f32_32x32x16_bf16 v[16:31], v[128:131], v[80:83], v[16:31]
	v_add_f32_e32 v243, v187, v243
	v_add_f32_e32 v242, v140, v242
	v_add_f32_e32 v243, v189, v243
	v_add_f32_e32 v242, v142, v242
	v_add_f32_e32 v243, v191, v243
	v_add_f32_e32 v242, v194, v242
	v_add_f32_e32 v243, v193, v243
	s_waitcnt lgkmcnt(0)
	v_mfma_f32_32x32x16_bf16 v[0:15], v[88:91], v[80:83], v[0:15]
	v_cvt_pk_bf16_f32 v80, v133, v135
	v_cvt_pk_bf16_f32 v81, v137, v139
	v_cvt_pk_bf16_f32 v82, v141, v143
	v_cvt_pk_bf16_f32 v83, v195, v197
	v_add_f32_e32 v242, v196, v242
	v_add_f32_e32 v243, v133, v243
	s_waitcnt lgkmcnt(12)
	v_mfma_f32_32x32x16_bf16 v[48:63], v[108:111], v[80:83], v[48:63]
	v_add_f32_e32 v243, v135, v243
	v_add_f32_e32 v243, v137, v243
	s_waitcnt lgkmcnt(6)
	v_mfma_f32_32x32x16_bf16 v[32:47], v[230:233], v[80:83], v[32:47]
	v_add_f32_e32 v243, v139, v243
	v_add_f32_e32 v243, v141, v243
	s_waitcnt lgkmcnt(4)
	v_mfma_f32_32x32x16_bf16 v[16:31], v[234:237], v[80:83], v[16:31]
	v_add_f32_e32 v243, v143, v243
	v_add_f32_e32 v243, v195, v243
	s_waitcnt lgkmcnt(2)
	v_mfma_f32_32x32x16_bf16 v[0:15], v[238:241], v[80:83], v[0:15]
	v_add_f32_e32 v243, v197, v243
	v_add_f32_e32 v242, v242, v243
	v_add_f32_e32 v176, v176, v242
